# quarter-unit K loop (four half-stage slots): two barriers per K step instead of four, counted vmcnt wait moved next to the fragment-read wait
# baseline (speedup 1.0000x reference)
.Lq5_be:
	s_add_i32 s77, s77, 2
	s_add_u32 s34, s34, 0x100
	s_addc_u32 s35, s35, 0
	s_add_u32 s18, s18, 0x100
	s_addc_u32 s41, s41, 0
	s_cmp_gt_u32 s77, 13
	s_cbranch_scc1 .Lq5_exit
.Lq5_top:
	ds_read_b128 v[148:151], v214
	ds_read_b128 v[152:155], v214 offset:1024
	ds_read_b128 v[156:159], v214 offset:2048
	ds_read_b128 v[160:163], v214 offset:3072
	v_lshl_add_u64 v[2:3], s[34:35], 0, v[200:201]
	s_add_i32 m0, s48, 0xc000
	ds_read_b128 v[188:191], v216
	ds_read_b128 v[192:195], v216 offset:1024
	ds_read_b128 v[180:183], v216 offset:2048
	ds_read_b128 v[184:187], v216 offset:3072
	ds_read_b128 v[172:175], v216 offset:4096
	ds_read_b128 v[176:179], v216 offset:5120
	ds_read_b128 v[164:167], v216 offset:6144
	ds_read_b128 v[168:171], v216 offset:7168
	v_lshl_add_u64 v[2:3], s[34:35], 0, v[202:203]
	s_add_i32 m0, s48, 0xe000
	s_nop 0
	s_setprio 1
	v_mfma_f32_16x16x32_bf16 v[128:131], v[4:7], v[44:47], v[128:131]
	v_mfma_f32_16x16x32_bf16 v[124:127], v[12:15], v[44:47], v[124:127]
	v_mfma_f32_16x16x32_bf16 v[120:123], v[4:7], v[36:39], v[120:123]
	v_mfma_f32_16x16x32_bf16 v[116:119], v[12:15], v[36:39], v[116:119]
	v_mfma_f32_16x16x32_bf16 v[104:107], v[4:7], v[28:31], v[104:107]
	v_mfma_f32_16x16x32_bf16 v[100:103], v[12:15], v[28:31], v[100:103]
	s_setprio 0
	v_cmp_ne_u32_e64 s[2:3], 1, v217
	s_andn2_b64 vcc, exec, s[26:27]
	s_add_u32 s56, s34, 0xfff80080
	s_addc_u32 s57, s35, -1
	s_cmp_eq_u32 s77, 10
	s_cselect_b32 s59, s39, s57
	s_cselect_b32 s58, s38, s56
	s_cselect_b32 s57, s47, s41
	s_cselect_b32 s56, s46, s18
	s_setprio 1
	v_mfma_f32_16x16x32_bf16 v[88:91], v[4:7], v[20:23], v[88:91]
	v_mfma_f32_16x16x32_bf16 v[84:87], v[12:15], v[20:23], v[84:87]
	v_mfma_f32_16x16x32_bf16 v[128:131], v[8:11], v[48:51], v[128:131]
	v_mfma_f32_16x16x32_bf16 v[124:127], v[16:19], v[48:51], v[124:127]
	v_mfma_f32_16x16x32_bf16 v[120:123], v[8:11], v[40:43], v[120:123]
	v_mfma_f32_16x16x32_bf16 v[116:119], v[16:19], v[40:43], v[116:119]
	s_setprio 0
	s_waitcnt lgkmcnt(0)
	s_waitcnt vmcnt(8)
	s_barrier
	s_setprio 1
	v_mfma_f32_16x16x32_bf16 v[104:107], v[8:11], v[32:35], v[104:107]
	v_mfma_f32_16x16x32_bf16 v[100:103], v[16:19], v[32:35], v[100:103]
	v_mfma_f32_16x16x32_bf16 v[88:91], v[8:11], v[24:27], v[88:91]
	v_mfma_f32_16x16x32_bf16 v[84:87], v[16:19], v[24:27], v[84:87]
	s_setprio 0
	s_barrier
	s_mov_b32 m0, s49
	v_lshl_add_u64 v[2:3], s[56:57], 0, v[198:199]
	s_add_u32 s78, s56, 0x80000
	global_load_lds_dwordx4 v[2:3], off
	v_lshl_add_u64 v[204:205], s[56:57], 0, v[196:197]
	s_mov_b32 m0, s50
	s_addc_u32 s79, s57, 0
	global_load_lds_dwordx4 v[204:205], off
	v_lshl_add_u64 v[206:207], s[78:79], 0, v[198:199]
	s_mov_b32 m0, s51
	v_lshl_add_u64 v[208:209], s[58:59], 0, v[196:197]
	v_lshl_add_u64 v[206:207], s[78:79], 0, v[196:197]
	s_mov_b32 m0, s60
	s_and_b64 vcc, exec, s[2:3]
	v_lshl_add_u64 v[206:207], s[58:59], 0, v[198:199]
	s_mov_b32 m0, s48
	s_nop 0
	global_load_lds_dwordx4 v[206:207], off
	s_mov_b32 m0, s61
	s_nop 0
	global_load_lds_dwordx4 v[208:209], off
	v_add_u32_e32 v1, 0x18000, v213
	ds_read_b128 v[4:7], v1
	ds_read_b128 v[8:11], v1 offset:1024
	ds_read_b128 v[12:15], v1 offset:2048
	ds_read_b128 v[16:19], v1 offset:3072
	v_add_u32_e32 v1, 0x1c000, v213
	s_add_u32 s58, s58, 0x80000
	s_addc_u32 s59, s59, 0
	s_mov_b32 m0, s62
	v_lshl_add_u64 v[218:219], s[58:59], 0, v[198:199]
	ds_read_b128 v[44:47], v216 offset:32768
	ds_read_b128 v[48:51], v216 offset:33792
	ds_read_b128 v[36:39], v216 offset:34816
	ds_read_b128 v[40:43], v216 offset:35840
	ds_read_b128 v[28:31], v216 offset:36864
	ds_read_b128 v[32:35], v216 offset:37888
	ds_read_b128 v[20:23], v216 offset:38912
	ds_read_b128 v[24:27], v216 offset:39936
	v_lshl_add_u64 v[218:219], s[58:59], 0, v[196:197]
	s_mov_b32 m0, s63
	s_nop 0
	s_setprio 1
	v_mfma_f32_16x16x32_bf16 v[128:131], v[148:151], v[188:191], v[128:131]
	v_mfma_f32_16x16x32_bf16 v[124:127], v[156:159], v[188:191], v[124:127]
	v_mfma_f32_16x16x32_bf16 v[120:123], v[148:151], v[180:183], v[120:123]
	v_mfma_f32_16x16x32_bf16 v[116:119], v[156:159], v[180:183], v[116:119]
	v_mfma_f32_16x16x32_bf16 v[104:107], v[148:151], v[172:175], v[104:107]
	v_mfma_f32_16x16x32_bf16 v[100:103], v[156:159], v[172:175], v[100:103]
	s_setprio 0
	s_and_b64 vcc, exec, s[2:3]
	s_setprio 1
	v_mfma_f32_16x16x32_bf16 v[88:91], v[148:151], v[164:167], v[88:91]
	v_mfma_f32_16x16x32_bf16 v[84:87], v[156:159], v[164:167], v[84:87]
	v_mfma_f32_16x16x32_bf16 v[128:131], v[152:155], v[192:195], v[128:131]
	v_mfma_f32_16x16x32_bf16 v[124:127], v[160:163], v[192:195], v[124:127]
	v_mfma_f32_16x16x32_bf16 v[120:123], v[152:155], v[184:187], v[120:123]
	v_mfma_f32_16x16x32_bf16 v[116:119], v[160:163], v[184:187], v[116:119]
	s_setprio 0
	s_waitcnt lgkmcnt(0)
	s_waitcnt vmcnt(8)
	s_barrier
	s_setprio 1
	v_mfma_f32_16x16x32_bf16 v[104:107], v[152:155], v[176:179], v[104:107]
	v_mfma_f32_16x16x32_bf16 v[100:103], v[160:163], v[176:179], v[100:103]
	v_mfma_f32_16x16x32_bf16 v[88:91], v[152:155], v[168:171], v[88:91]
	v_mfma_f32_16x16x32_bf16 v[84:87], v[160:163], v[168:171], v[84:87]
	s_setprio 0
	s_barrier
	s_mov_b32 m0, s66
	v_lshl_add_u64 v[2:3], v[2:3], 0, s[16:17]
	s_add_u32 s56, s56, 0x80080
	global_load_lds_dwordx4 v[2:3], off
	v_lshl_add_u64 v[2:3], v[204:205], 0, s[16:17]
	s_mov_b32 m0, s67
	s_addc_u32 s57, s57, 0
	global_load_lds_dwordx4 v[2:3], off
	v_lshl_add_u64 v[2:3], s[56:57], 0, v[198:199]
	s_mov_b32 m0, s70
	s_and_b64 vcc, exec, s[2:3]
	v_lshl_add_u64 v[2:3], s[56:57], 0, v[196:197]
	s_mov_b32 m0, s71
	s_nop 0
	v_lshl_add_u64 v[2:3], v[206:207], 0, s[16:17]
	s_mov_b32 m0, s68
	s_nop 0
	global_load_lds_dwordx4 v[2:3], off
	v_lshl_add_u64 v[2:3], v[208:209], 0, s[16:17]
	s_mov_b32 m0, s69
	s_nop 0
	global_load_lds_dwordx4 v[2:3], off
	s_add_i32 s77, s77, 2
	s_add_u32 s34, s34, 0x100
	s_addc_u32 s35, s35, 0
	s_add_u32 s18, s18, 0x100
	s_addc_u32 s41, s41, 0
	s_cmp_gt_u32 s77, 13
	ds_read_b128 v[148:151], v215
	ds_read_b128 v[152:155], v215 offset:1024
	ds_read_b128 v[156:159], v215 offset:2048
	ds_read_b128 v[160:163], v215 offset:3072
	v_lshl_add_u64 v[2:3], s[34:35], 0, v[200:201]
	s_add_i32 m0, s48, 0xc000
	ds_read_b128 v[188:191], v216 offset:16384
	ds_read_b128 v[192:195], v216 offset:17408
	ds_read_b128 v[180:183], v216 offset:18432
	ds_read_b128 v[184:187], v216 offset:19456
	ds_read_b128 v[172:175], v216 offset:20480
	ds_read_b128 v[176:179], v216 offset:21504
	ds_read_b128 v[164:167], v216 offset:22528
	ds_read_b128 v[168:171], v216 offset:23552
	v_lshl_add_u64 v[2:3], s[34:35], 0, v[202:203]
	s_add_i32 m0, s48, 0xe000
	s_nop 0
	s_setprio 1
	v_mfma_f32_16x16x32_bf16 v[128:131], v[4:7], v[44:47], v[128:131]
	v_mfma_f32_16x16x32_bf16 v[124:127], v[12:15], v[44:47], v[124:127]
	v_mfma_f32_16x16x32_bf16 v[120:123], v[4:7], v[36:39], v[120:123]
	v_mfma_f32_16x16x32_bf16 v[116:119], v[12:15], v[36:39], v[116:119]
	v_mfma_f32_16x16x32_bf16 v[104:107], v[4:7], v[28:31], v[104:107]
	v_mfma_f32_16x16x32_bf16 v[100:103], v[12:15], v[28:31], v[100:103]
	s_setprio 0
	v_cmp_ne_u32_e64 s[2:3], 1, v217
	s_andn2_b64 vcc, exec, s[26:27]
	s_add_u32 s56, s34, 0xfff80080
	s_addc_u32 s57, s35, -1
	s_cmp_eq_u32 s77, 12
	s_cselect_b32 s59, s39, s57
	s_cselect_b32 s58, s38, s56
	s_cselect_b32 s57, s47, s41
	s_cselect_b32 s56, s46, s18
	s_setprio 1
	v_mfma_f32_16x16x32_bf16 v[88:91], v[4:7], v[20:23], v[88:91]
	v_mfma_f32_16x16x32_bf16 v[84:87], v[12:15], v[20:23], v[84:87]
	v_mfma_f32_16x16x32_bf16 v[128:131], v[8:11], v[48:51], v[128:131]
	v_mfma_f32_16x16x32_bf16 v[124:127], v[16:19], v[48:51], v[124:127]
	v_mfma_f32_16x16x32_bf16 v[120:123], v[8:11], v[40:43], v[120:123]
	v_mfma_f32_16x16x32_bf16 v[116:119], v[16:19], v[40:43], v[116:119]
	s_setprio 0
	s_waitcnt lgkmcnt(0)
	s_waitcnt vmcnt(8)
	s_barrier
	s_setprio 1
	v_mfma_f32_16x16x32_bf16 v[104:107], v[8:11], v[32:35], v[104:107]
	v_mfma_f32_16x16x32_bf16 v[100:103], v[16:19], v[32:35], v[100:103]
	v_mfma_f32_16x16x32_bf16 v[88:91], v[8:11], v[24:27], v[88:91]
	v_mfma_f32_16x16x32_bf16 v[84:87], v[16:19], v[24:27], v[84:87]
	s_setprio 0
	s_barrier
	s_cmp_eq_u32 s77, 12
	s_cbranch_scc1 .Lq5_o_n0
	s_mov_b32 m0, s51
	v_lshl_add_u64 v[2:3], s[56:57], 0, v[198:199]
	s_add_u32 s78, s56, 0x80000
	global_load_lds_dwordx4 v[2:3], off
	v_lshl_add_u64 v[204:205], s[56:57], 0, v[196:197]
	s_mov_b32 m0, s60
	s_addc_u32 s79, s57, 0
	global_load_lds_dwordx4 v[204:205], off
	v_lshl_add_u64 v[206:207], s[78:79], 0, v[198:199]
	s_mov_b32 m0, s66
	v_lshl_add_u64 v[208:209], s[58:59], 0, v[196:197]
	v_lshl_add_u64 v[206:207], s[78:79], 0, v[196:197]
	s_mov_b32 m0, s67
	s_and_b64 vcc, exec, s[2:3]
	v_lshl_add_u64 v[206:207], s[58:59], 0, v[198:199]
	s_mov_b32 m0, s62
	s_nop 0
	global_load_lds_dwordx4 v[206:207], off
	s_mov_b32 m0, s63
	s_nop 0
	global_load_lds_dwordx4 v[208:209], off
.Lq5_o_n0:
	v_add_u32_e32 v1, 0x1c000, v213
	ds_read_b128 v[4:7], v1
	ds_read_b128 v[8:11], v1 offset:1024
	ds_read_b128 v[12:15], v1 offset:2048
	ds_read_b128 v[16:19], v1 offset:3072
	v_add_u32_e32 v1, 0x1c000, v213
	s_add_u32 s58, s58, 0x80000
	s_addc_u32 s59, s59, 0
	s_mov_b32 m0, s62
	v_lshl_add_u64 v[218:219], s[58:59], 0, v[198:199]
	ds_read_b128 v[44:47], v216 offset:49152
	ds_read_b128 v[48:51], v216 offset:50176
	ds_read_b128 v[36:39], v216 offset:51200
	ds_read_b128 v[40:43], v216 offset:52224
	ds_read_b128 v[28:31], v216 offset:53248
	ds_read_b128 v[32:35], v216 offset:54272
	ds_read_b128 v[20:23], v216 offset:55296
	ds_read_b128 v[24:27], v216 offset:56320
	v_lshl_add_u64 v[218:219], s[58:59], 0, v[196:197]
	s_mov_b32 m0, s63
	s_nop 0
	s_setprio 1
	v_mfma_f32_16x16x32_bf16 v[128:131], v[148:151], v[188:191], v[128:131]
	v_mfma_f32_16x16x32_bf16 v[124:127], v[156:159], v[188:191], v[124:127]
	v_mfma_f32_16x16x32_bf16 v[120:123], v[148:151], v[180:183], v[120:123]
	v_mfma_f32_16x16x32_bf16 v[116:119], v[156:159], v[180:183], v[116:119]
	v_mfma_f32_16x16x32_bf16 v[104:107], v[148:151], v[172:175], v[104:107]
	v_mfma_f32_16x16x32_bf16 v[100:103], v[156:159], v[172:175], v[100:103]
	s_setprio 0
	s_and_b64 vcc, exec, s[2:3]
	s_setprio 1
	v_mfma_f32_16x16x32_bf16 v[88:91], v[148:151], v[164:167], v[88:91]
	v_mfma_f32_16x16x32_bf16 v[84:87], v[156:159], v[164:167], v[84:87]
	v_mfma_f32_16x16x32_bf16 v[128:131], v[152:155], v[192:195], v[128:131]
	v_mfma_f32_16x16x32_bf16 v[124:127], v[160:163], v[192:195], v[124:127]
	v_mfma_f32_16x16x32_bf16 v[120:123], v[152:155], v[184:187], v[120:123]
	v_mfma_f32_16x16x32_bf16 v[116:119], v[160:163], v[184:187], v[116:119]
	s_setprio 0
	s_waitcnt lgkmcnt(0)
	s_waitcnt vmcnt(8)
	s_cmp_eq_u32 s77, 12
	s_cbranch_scc0 .Lq5_o_w
	s_waitcnt vmcnt(4)
.Lq5_o_w:
	s_barrier
	s_setprio 1
	v_mfma_f32_16x16x32_bf16 v[104:107], v[152:155], v[176:179], v[104:107]
	v_mfma_f32_16x16x32_bf16 v[100:103], v[160:163], v[176:179], v[100:103]
	v_mfma_f32_16x16x32_bf16 v[88:91], v[152:155], v[168:171], v[88:91]
	v_mfma_f32_16x16x32_bf16 v[84:87], v[160:163], v[168:171], v[84:87]
	s_setprio 0
	s_barrier
	s_cmp_eq_u32 s77, 12
	s_cbranch_scc1 .Lq5_o_n1
	s_mov_b32 m0, s70
	v_lshl_add_u64 v[2:3], v[2:3], 0, s[16:17]
	s_add_u32 s56, s56, 0x80080
	global_load_lds_dwordx4 v[2:3], off
	v_lshl_add_u64 v[2:3], v[204:205], 0, s[16:17]
	s_mov_b32 m0, s71
	s_addc_u32 s57, s57, 0
	global_load_lds_dwordx4 v[2:3], off
	v_lshl_add_u64 v[2:3], s[56:57], 0, v[198:199]
	s_add_i32 m0, s48, 0x20000
	s_and_b64 vcc, exec, s[2:3]
	v_lshl_add_u64 v[2:3], s[56:57], 0, v[196:197]
	s_add_i32 m0, s48, 0x22000
	s_nop 0
	v_lshl_add_u64 v[2:3], v[206:207], 0, s[16:17]
	s_add_i32 m0, s48, 0xc000
	s_nop 0
	global_load_lds_dwordx4 v[2:3], off
	v_lshl_add_u64 v[2:3], v[208:209], 0, s[16:17]
	s_add_i32 m0, s48, 0xe000
	s_nop 0
	global_load_lds_dwordx4 v[2:3], off

.Lq6_be:
	s_add_i32 s84, s84, 2
	s_add_u32 s38, s38, 0x100
	s_addc_u32 s39, s39, 0
	s_add_u32 s16, s16, 0x100
	s_addc_u32 s27, s27, 0
	s_cmp_gt_u32 s84, 29
	s_cbranch_scc1 .Lq6_exit
.Lq6_top:
	ds_read_b128 v[180:183], v247
	ds_read_b128 v[184:187], v247 offset:1024
	ds_read_b128 v[188:191], v247 offset:2048
	ds_read_b128 v[192:195], v247 offset:3072
	v_lshl_add_u64 v[2:3], s[38:39], 0, v[232:233]
	s_add_i32 m0, s44, 0xc000
	ds_read_b128 v[220:223], v249
	ds_read_b128 v[224:227], v249 offset:1024
	ds_read_b128 v[212:215], v249 offset:2048
	ds_read_b128 v[216:219], v249 offset:3072
	ds_read_b128 v[204:207], v249 offset:4096
	ds_read_b128 v[208:211], v249 offset:5120
	ds_read_b128 v[196:199], v249 offset:6144
	ds_read_b128 v[200:203], v249 offset:7168
	v_lshl_add_u64 v[2:3], s[38:39], 0, v[234:235]
	s_add_i32 m0, s44, 0xe000
	s_nop 0
	s_setprio 1
	v_mfma_f32_16x16x32_bf16 v[68:71], v[4:7], v[44:47], v[160:163]
	v_mfma_f32_16x16x32_bf16 v[72:75], v[12:15], v[44:47], v[156:159]
	v_mfma_f32_16x16x32_bf16 v[76:79], v[4:7], v[36:39], v[152:155]
	v_mfma_f32_16x16x32_bf16 v[80:83], v[12:15], v[36:39], v[148:151]
	v_mfma_f32_16x16x32_bf16 v[84:87], v[4:7], v[28:31], v[136:139]
	v_mfma_f32_16x16x32_bf16 v[92:95], v[12:15], v[28:31], v[132:135]
	s_setprio 0
	v_cmp_ne_u32_e64 s[4:5], 1, v251
	s_andn2_b64 vcc, exec, s[34:35]
	s_add_u32 s40, s38, 0xfff80080
	s_addc_u32 s41, s39, -1
	s_cmp_eq_u32 s84, 26
	s_cselect_b32 s47, s29, s41
	s_cselect_b32 s46, s28, s40
	s_cselect_b32 s41, s37, s27
	s_cselect_b32 s40, s36, s16
	s_setprio 1
	v_mfma_f32_16x16x32_bf16 v[96:99], v[4:7], v[20:23], v[120:123]
	v_mfma_f32_16x16x32_bf16 v[100:103], v[12:15], v[20:23], v[112:115]
	v_mfma_f32_16x16x32_bf16 v[68:71], v[8:11], v[48:51], v[68:71]
	v_mfma_f32_16x16x32_bf16 v[72:75], v[16:19], v[48:51], v[72:75]
	v_mfma_f32_16x16x32_bf16 v[76:79], v[8:11], v[40:43], v[76:79]
	v_mfma_f32_16x16x32_bf16 v[80:83], v[16:19], v[40:43], v[80:83]
	s_setprio 0
	s_waitcnt lgkmcnt(0)
	s_waitcnt vmcnt(8)
	s_barrier
	s_setprio 1
	v_mfma_f32_16x16x32_bf16 v[84:87], v[8:11], v[32:35], v[84:87]
	v_mfma_f32_16x16x32_bf16 v[92:95], v[16:19], v[32:35], v[92:95]
	v_mfma_f32_16x16x32_bf16 v[96:99], v[8:11], v[24:27], v[96:99]
	v_mfma_f32_16x16x32_bf16 v[100:103], v[16:19], v[24:27], v[100:103]
	s_setprio 0
	s_barrier
	s_mov_b32 m0, s45
	v_lshl_add_u64 v[2:3], s[40:41], 0, v[230:231]
	s_add_u32 s86, s40, 0x80000
	global_load_lds_dwordx4 v[2:3], off
	v_lshl_add_u64 v[236:237], s[40:41], 0, v[228:229]
	s_mov_b32 m0, s48
	s_addc_u32 s87, s41, 0
	global_load_lds_dwordx4 v[236:237], off
	v_lshl_add_u64 v[54:55], s[86:87], 0, v[230:231]
	s_mov_b32 m0, s49
	v_lshl_add_u64 v[238:239], s[46:47], 0, v[230:231]
	v_lshl_add_u64 v[54:55], s[86:87], 0, v[228:229]
	s_mov_b32 m0, s50
	v_lshl_add_u64 v[240:241], s[46:47], 0, v[228:229]
	s_mov_b32 m0, s44
	s_and_b64 vcc, exec, s[4:5]
	global_load_lds_dwordx4 v[238:239], off
	s_mov_b32 m0, s51
	s_nop 0
	global_load_lds_dwordx4 v[240:241], off
	v_add_u32_e32 v1, 0x18000, v246
	ds_read_b128 v[4:7], v1
	ds_read_b128 v[8:11], v1 offset:1024
	ds_read_b128 v[12:15], v1 offset:2048
	ds_read_b128 v[16:19], v1 offset:3072
	v_add_u32_e32 v1, 0x1c000, v246
	s_add_u32 s46, s46, 0x80000
	s_addc_u32 s47, s47, 0
	s_mov_b32 m0, s56
	v_lshl_add_u64 v[112:113], s[46:47], 0, v[230:231]
	ds_read_b128 v[44:47], v249 offset:32768
	ds_read_b128 v[48:51], v249 offset:33792
	ds_read_b128 v[36:39], v249 offset:34816
	ds_read_b128 v[40:43], v249 offset:35840
	ds_read_b128 v[28:31], v249 offset:36864
	ds_read_b128 v[32:35], v249 offset:37888
	ds_read_b128 v[20:23], v249 offset:38912
	ds_read_b128 v[24:27], v249 offset:39936
	v_lshl_add_u64 v[112:113], s[46:47], 0, v[228:229]
	s_mov_b32 m0, s57
	s_nop 0
	s_setprio 1
	v_mfma_f32_16x16x32_bf16 v[68:71], v[180:183], v[220:223], v[68:71]
	v_mfma_f32_16x16x32_bf16 v[160:163], v[184:187], v[224:227], v[68:71]
	v_mfma_f32_16x16x32_bf16 v[68:71], v[188:191], v[220:223], v[72:75]
	v_mfma_f32_16x16x32_bf16 v[156:159], v[192:195], v[224:227], v[68:71]
	v_mfma_f32_16x16x32_bf16 v[68:71], v[180:183], v[212:215], v[76:79]
	v_mfma_f32_16x16x32_bf16 v[152:155], v[184:187], v[216:219], v[68:71]
	s_setprio 0
	s_and_b64 vcc, exec, s[4:5]
	s_setprio 1
	v_mfma_f32_16x16x32_bf16 v[68:71], v[188:191], v[212:215], v[80:83]
	v_mfma_f32_16x16x32_bf16 v[148:151], v[192:195], v[216:219], v[68:71]
	v_mfma_f32_16x16x32_bf16 v[68:71], v[180:183], v[204:207], v[84:87]
	v_mfma_f32_16x16x32_bf16 v[136:139], v[184:187], v[208:211], v[68:71]
	v_mfma_f32_16x16x32_bf16 v[68:71], v[188:191], v[204:207], v[92:95]
	v_mfma_f32_16x16x32_bf16 v[132:135], v[192:195], v[208:211], v[68:71]
	s_setprio 0
	s_waitcnt lgkmcnt(0)
	s_waitcnt vmcnt(8)
	s_barrier
	s_setprio 1
	v_mfma_f32_16x16x32_bf16 v[68:71], v[180:183], v[196:199], v[96:99]
	v_mfma_f32_16x16x32_bf16 v[120:123], v[184:187], v[200:203], v[68:71]
	v_mfma_f32_16x16x32_bf16 v[68:71], v[188:191], v[196:199], v[100:103]
	v_mfma_f32_16x16x32_bf16 v[112:115], v[192:195], v[200:203], v[68:71]
	s_setprio 0
	s_barrier
	s_mov_b32 m0, s61
	v_lshl_add_u64 v[2:3], v[2:3], 0, s[14:15]
	s_add_u32 s40, s40, 0x80080
	global_load_lds_dwordx4 v[2:3], off
	v_lshl_add_u64 v[2:3], v[236:237], 0, s[14:15]
	s_mov_b32 m0, s62
	s_addc_u32 s41, s41, 0
	global_load_lds_dwordx4 v[2:3], off
	v_lshl_add_u64 v[2:3], s[40:41], 0, v[230:231]
	s_mov_b32 m0, s65
	s_and_b64 vcc, exec, s[4:5]
	v_lshl_add_u64 v[2:3], s[40:41], 0, v[228:229]
	s_mov_b32 m0, s66
	s_nop 0
	v_lshl_add_u64 v[2:3], v[238:239], 0, s[14:15]
	s_mov_b32 m0, s63
	s_nop 0
	global_load_lds_dwordx4 v[2:3], off
	v_lshl_add_u64 v[2:3], v[240:241], 0, s[14:15]
	s_mov_b32 m0, s64
	s_nop 0
	global_load_lds_dwordx4 v[2:3], off
	s_add_i32 s84, s84, 2
	s_add_u32 s38, s38, 0x100
	s_addc_u32 s39, s39, 0
	s_add_u32 s16, s16, 0x100
	s_addc_u32 s27, s27, 0
	s_cmp_gt_u32 s84, 29
	ds_read_b128 v[180:183], v248
	ds_read_b128 v[184:187], v248 offset:1024
	ds_read_b128 v[188:191], v248 offset:2048
	ds_read_b128 v[192:195], v248 offset:3072
	v_lshl_add_u64 v[2:3], s[38:39], 0, v[232:233]
	s_add_i32 m0, s44, 0xc000
	ds_read_b128 v[220:223], v249 offset:16384
	ds_read_b128 v[224:227], v249 offset:17408
	ds_read_b128 v[212:215], v249 offset:18432
	ds_read_b128 v[216:219], v249 offset:19456
	ds_read_b128 v[204:207], v249 offset:20480
	ds_read_b128 v[208:211], v249 offset:21504
	ds_read_b128 v[196:199], v249 offset:22528
	ds_read_b128 v[200:203], v249 offset:23552
	v_lshl_add_u64 v[2:3], s[38:39], 0, v[234:235]
	s_add_i32 m0, s44, 0xe000
	s_nop 0
	s_setprio 1
	v_mfma_f32_16x16x32_bf16 v[68:71], v[4:7], v[44:47], v[160:163]
	v_mfma_f32_16x16x32_bf16 v[72:75], v[12:15], v[44:47], v[156:159]
	v_mfma_f32_16x16x32_bf16 v[76:79], v[4:7], v[36:39], v[152:155]
	v_mfma_f32_16x16x32_bf16 v[80:83], v[12:15], v[36:39], v[148:151]
	v_mfma_f32_16x16x32_bf16 v[84:87], v[4:7], v[28:31], v[136:139]
	v_mfma_f32_16x16x32_bf16 v[92:95], v[12:15], v[28:31], v[132:135]
	s_setprio 0
	v_cmp_ne_u32_e64 s[4:5], 1, v251
	s_andn2_b64 vcc, exec, s[34:35]
	s_add_u32 s40, s38, 0xfff80080
	s_addc_u32 s41, s39, -1
	s_cmp_eq_u32 s84, 28
	s_cselect_b32 s47, s29, s41
	s_cselect_b32 s46, s28, s40
	s_cselect_b32 s41, s37, s27
	s_cselect_b32 s40, s36, s16
	s_setprio 1
	v_mfma_f32_16x16x32_bf16 v[96:99], v[4:7], v[20:23], v[120:123]
	v_mfma_f32_16x16x32_bf16 v[100:103], v[12:15], v[20:23], v[112:115]
	v_mfma_f32_16x16x32_bf16 v[68:71], v[8:11], v[48:51], v[68:71]
	v_mfma_f32_16x16x32_bf16 v[72:75], v[16:19], v[48:51], v[72:75]
	v_mfma_f32_16x16x32_bf16 v[76:79], v[8:11], v[40:43], v[76:79]
	v_mfma_f32_16x16x32_bf16 v[80:83], v[16:19], v[40:43], v[80:83]
	s_setprio 0
	s_waitcnt lgkmcnt(0)
	s_waitcnt vmcnt(8)
	s_barrier
	s_setprio 1
	v_mfma_f32_16x16x32_bf16 v[84:87], v[8:11], v[32:35], v[84:87]
	v_mfma_f32_16x16x32_bf16 v[92:95], v[16:19], v[32:35], v[92:95]
	v_mfma_f32_16x16x32_bf16 v[96:99], v[8:11], v[24:27], v[96:99]
	v_mfma_f32_16x16x32_bf16 v[100:103], v[16:19], v[24:27], v[100:103]
	s_setprio 0
	s_barrier
	s_cmp_eq_u32 s84, 28
	s_cbranch_scc1 .Lq6_o_n0
	s_mov_b32 m0, s49
	v_lshl_add_u64 v[2:3], s[40:41], 0, v[230:231]
	s_add_u32 s86, s40, 0x80000
	global_load_lds_dwordx4 v[2:3], off
	v_lshl_add_u64 v[236:237], s[40:41], 0, v[228:229]
	s_mov_b32 m0, s50
	s_addc_u32 s87, s41, 0
	global_load_lds_dwordx4 v[236:237], off
	v_lshl_add_u64 v[54:55], s[86:87], 0, v[230:231]
	s_mov_b32 m0, s61
	v_lshl_add_u64 v[238:239], s[46:47], 0, v[230:231]
	v_lshl_add_u64 v[54:55], s[86:87], 0, v[228:229]
	s_mov_b32 m0, s62
	v_lshl_add_u64 v[240:241], s[46:47], 0, v[228:229]
	s_mov_b32 m0, s56
	s_and_b64 vcc, exec, s[4:5]
	global_load_lds_dwordx4 v[238:239], off
	s_mov_b32 m0, s57
	s_nop 0
	global_load_lds_dwordx4 v[240:241], off
.Lq6_o_n0:
	v_add_u32_e32 v1, 0x1c000, v246
	ds_read_b128 v[4:7], v1
	ds_read_b128 v[8:11], v1 offset:1024
	ds_read_b128 v[12:15], v1 offset:2048
	ds_read_b128 v[16:19], v1 offset:3072
	v_add_u32_e32 v1, 0x1c000, v246
	s_add_u32 s46, s46, 0x80000
	s_addc_u32 s47, s47, 0
	s_mov_b32 m0, s56
	v_lshl_add_u64 v[112:113], s[46:47], 0, v[230:231]
	ds_read_b128 v[44:47], v249 offset:49152
	ds_read_b128 v[48:51], v249 offset:50176
	ds_read_b128 v[36:39], v249 offset:51200
	ds_read_b128 v[40:43], v249 offset:52224
	ds_read_b128 v[28:31], v249 offset:53248
	ds_read_b128 v[32:35], v249 offset:54272
	ds_read_b128 v[20:23], v249 offset:55296
	ds_read_b128 v[24:27], v249 offset:56320
	v_lshl_add_u64 v[112:113], s[46:47], 0, v[228:229]
	s_mov_b32 m0, s57
	s_nop 0
	s_setprio 1
	v_mfma_f32_16x16x32_bf16 v[68:71], v[180:183], v[220:223], v[68:71]
	v_mfma_f32_16x16x32_bf16 v[160:163], v[184:187], v[224:227], v[68:71]
	v_mfma_f32_16x16x32_bf16 v[68:71], v[188:191], v[220:223], v[72:75]
	v_mfma_f32_16x16x32_bf16 v[156:159], v[192:195], v[224:227], v[68:71]
	v_mfma_f32_16x16x32_bf16 v[68:71], v[180:183], v[212:215], v[76:79]
	v_mfma_f32_16x16x32_bf16 v[152:155], v[184:187], v[216:219], v[68:71]
	s_setprio 0
	s_and_b64 vcc, exec, s[4:5]
	s_setprio 1
	v_mfma_f32_16x16x32_bf16 v[68:71], v[188:191], v[212:215], v[80:83]
	v_mfma_f32_16x16x32_bf16 v[148:151], v[192:195], v[216:219], v[68:71]
	v_mfma_f32_16x16x32_bf16 v[68:71], v[180:183], v[204:207], v[84:87]
	v_mfma_f32_16x16x32_bf16 v[136:139], v[184:187], v[208:211], v[68:71]
	v_mfma_f32_16x16x32_bf16 v[68:71], v[188:191], v[204:207], v[92:95]
	v_mfma_f32_16x16x32_bf16 v[132:135], v[192:195], v[208:211], v[68:71]
	s_setprio 0
	s_waitcnt lgkmcnt(0)
	s_waitcnt vmcnt(8)
	s_cmp_eq_u32 s84, 28
	s_cbranch_scc0 .Lq6_o_w
	s_waitcnt vmcnt(4)
.Lq6_o_w:
	s_barrier
	s_setprio 1
	v_mfma_f32_16x16x32_bf16 v[68:71], v[180:183], v[196:199], v[96:99]
	v_mfma_f32_16x16x32_bf16 v[120:123], v[184:187], v[200:203], v[68:71]
	v_mfma_f32_16x16x32_bf16 v[68:71], v[188:191], v[196:199], v[100:103]
	v_mfma_f32_16x16x32_bf16 v[112:115], v[192:195], v[200:203], v[68:71]
	s_setprio 0
	s_barrier
	s_cmp_eq_u32 s84, 28
	s_cbranch_scc1 .Lq6_o_n1
	s_mov_b32 m0, s65
	v_lshl_add_u64 v[2:3], v[2:3], 0, s[14:15]
	s_add_u32 s40, s40, 0x80080
	global_load_lds_dwordx4 v[2:3], off
	v_lshl_add_u64 v[2:3], v[236:237], 0, s[14:15]
	s_mov_b32 m0, s66
	s_addc_u32 s41, s41, 0
	global_load_lds_dwordx4 v[2:3], off
	v_lshl_add_u64 v[2:3], s[40:41], 0, v[230:231]
	s_add_i32 m0, s44, 0x20000
	s_and_b64 vcc, exec, s[4:5]
	v_lshl_add_u64 v[2:3], s[40:41], 0, v[228:229]
	s_add_i32 m0, s44, 0x22000
	s_nop 0
	v_lshl_add_u64 v[2:3], v[238:239], 0, s[14:15]
	s_add_i32 m0, s44, 0xc000
	s_nop 0
	global_load_lds_dwordx4 v[2:3], off
	v_lshl_add_u64 v[2:3], v[240:241], 0, s[14:15]
	s_add_i32 m0, s44, 0xe000
	s_nop 0
	global_load_lds_dwordx4 v[2:3], off
